# attention phase: V-band loads issued in the softmax section as soon as their destination registers die (was: after the softmax, right before the barrier)
# baseline (speedup 1.0000x reference)
.LBB0_1419:
	s_waitcnt lgkmcnt(3)
	v_add_f32_e32 v20, v79, v80
	v_fmamk_f32 v20, v20, 0x3c800000, v106
	v_rsq_f32_e32 v20, v20
	v_max_i32_e32 v21, 8, v76
	v_add_u32_e32 v45, -8, v21
	s_max_i32 s0, s2, 4
	v_mul_f32_e32 v44, 0x3e38aa3b, v20
	v_pk_mul_f32 v[22:23], v[44:45], v[74:75] op_sel_hi:[0,1]
	s_waitcnt vmcnt(0)
	v_pk_mul_f32 v[22:23], v[36:37], v[22:23]
	v_pk_mul_f32 v[20:21], v[44:45], v[64:65] op_sel_hi:[0,1]
	v_cvt_pk_f16_f32 v24, v22, v23
	v_pk_mul_f32 v[22:23], v[44:45], v[60:61] op_sel_hi:[0,1]
	v_pk_mul_f32 v[20:21], v[40:41], v[20:21]
	v_pk_mul_f32 v[22:23], v[42:43], v[22:23]
	v_cvt_pk_f16_f32 v20, v20, v21
	v_cvt_pk_f16_f32 v21, v22, v23
	v_pk_mul_f32 v[22:23], v[44:45], v[62:63] op_sel_hi:[0,1]
	v_pk_mul_f32 v[22:23], v[38:39], v[22:23]
	v_pk_mul_f32 v[26:27], v[44:45], v[68:69] op_sel_hi:[0,1]
	v_cvt_pk_f16_f32 v25, v22, v23
	v_pk_mul_f32 v[22:23], v[44:45], v[66:67] op_sel_hi:[0,1]
	v_pk_mul_f32 v[26:27], v[28:29], v[26:27]
	v_pk_mul_f32 v[28:29], v[44:45], v[70:71] op_sel_hi:[0,1]
	v_pk_mul_f32 v[22:23], v[32:33], v[22:23]
	v_pk_mul_f32 v[28:29], v[34:35], v[28:29]
	s_add_i32 s0, s0, -4
	v_cvt_pk_f16_f32 v22, v22, v23
	v_cvt_pk_f16_f32 v23, v28, v29
	v_pk_mul_f32 v[28:29], v[44:45], v[72:73] op_sel_hi:[0,1]
	s_min_u32 s0, s0, 0x78
	v_pk_mul_f32 v[28:29], v[30:31], v[28:29]
	s_sub_i32 s3, s0, s41
	v_cvt_pk_f16_f32 v26, v26, v27
	v_cvt_pk_f16_f32 v27, v28, v29
	v_add_u32_e32 v64, s40, v101
	v_and_b32_e32 v29, -16, v77
	s_lshl_b32 s16, s3, 6
	v_add_u32_e32 v65, 0, v29
	v_add_u32_e32 v30, s16, v64
	s_waitcnt lgkmcnt(0)
	s_barrier
	v_mad_i32_i24 v38, v30, s25, v65
	ds_read_b128 v[30:33], v38
	ds_read_b128 v[34:37], v38 offset:64
	v_lshlrev_b32_e32 v100, 2, v78
	v_add_u32_e32 v42, s40, v100
	v_min_u32_e32 v60, 48, v45
	v_add_u32_e32 v28, 16, v42
	v_cmp_ge_i32_e32 vcc, v28, v60
	v_sub_u32_e32 v28, v28, v76
	v_max_i32_e32 v28, -15, v28
	v_add_u32_e32 v28, 15, v28
	s_sub_i32 s2, s0, s2
	v_min_u32_e32 v43, 30, v28
	v_sub_u32_e32 v28, v42, v76
	s_mulk_i32 s2, 0x7c
	v_max_i32_e32 v28, -15, v28
	s_add_i32 s2, s2, 0
	s_waitcnt lgkmcnt(1)
	v_mfma_f32_16x16x32_f16 v[30:33], v[30:33], v[24:27], 0
	v_add_u32_e32 v28, 15, v28
	s_add_i32 s45, s2, 0x26764
	v_min_u32_e32 v28, 30, v28
	v_lshl_add_u32 v62, v28, 2, s45
	ds_read2_b32 v[44:45], v62 offset1:31
	s_waitcnt lgkmcnt(1)
	v_mfma_f32_16x16x32_f16 v[30:33], v[34:37], v[20:23], v[30:33]
	v_or_b32_e32 v34, 1, v42
	v_add_u32_e32 v61, 16, v60
	v_cmp_ge_i32_e64 s[2:3], v42, v60
	v_cmp_lt_i32_e64 s[4:5], v42, v61
	s_and_b64 s[2:3], s[2:3], s[4:5]
	s_waitcnt lgkmcnt(0)
	s_nop 1
	v_add_f32_e32 v28, v30, v44
	v_sub_u32_e32 v30, v34, v76
	v_max_i32_e32 v30, -15, v30
	v_add_u32_e32 v30, 15, v30
	v_min_u32_e32 v30, 30, v30
	v_lshl_add_u32 v63, v30, 2, s45
	v_cndmask_b32_e64 v30, v107, 0, s[2:3]
	v_cmp_ge_i32_e64 s[2:3], v34, v60
	v_cmp_lt_i32_e64 s[4:5], v34, v61
	v_or_b32_e32 v34, 2, v42
	v_sub_u32_e32 v35, v34, v76
	ds_read2_b32 v[46:47], v63 offset1:31
	s_and_b64 s[2:3], s[2:3], s[4:5]
	v_max_i32_e32 v35, -15, v35
	v_or_b32_e32 v39, 3, v42
	v_add_f32_e32 v127, v30, v28
	v_cndmask_b32_e64 v28, v107, 0, s[2:3]
	v_add_u32_e32 v35, 15, v35
	v_cmp_ge_i32_e64 s[2:3], v34, v60
	v_cmp_lt_i32_e64 s[4:5], v34, v61
	v_sub_u32_e32 v34, v39, v76
	v_min_u32_e32 v35, 30, v35
	v_max_i32_e32 v34, -15, v34
	v_lshl_add_u32 v66, v35, 2, s45
	v_add_u32_e32 v34, 15, v34
	ds_read2_b32 v[48:49], v66 offset1:31
	v_min_u32_e32 v34, 30, v34
	s_waitcnt lgkmcnt(1)
	v_add_f32_e32 v31, v31, v46
	s_and_b64 s[2:3], s[2:3], s[4:5]
	v_lshl_add_u32 v67, v34, 2, s45
	v_add_f32_e32 v128, v28, v31
	v_cndmask_b32_e64 v31, v107, 0, s[2:3]
	ds_read2_b32 v[50:51], v67 offset1:31
	ds_read_b128 v[34:37], v38 offset:2304
	v_cmp_ge_i32_e64 s[2:3], v39, v60
	v_cmp_lt_i32_e64 s[4:5], v39, v61
	ds_read_b128 v[38:41], v38 offset:2368
	s_waitcnt lgkmcnt(3)
	v_add_f32_e32 v32, v32, v48
	s_and_b64 s[2:3], s[2:3], s[4:5]
	v_add_f32_e32 v129, v31, v32
	s_waitcnt lgkmcnt(2)
	v_add_f32_e32 v32, v33, v50
	v_cndmask_b32_e64 v154, v107, 0, s[2:3]
	v_add_f32_e32 v130, v154, v32
	s_waitcnt lgkmcnt(1)
	v_mfma_f32_16x16x32_f16 v[32:35], v[34:37], v[24:27], 0
	v_add_u32_e32 v37, 17, v42
	v_lshl_add_u32 v68, v43, 2, s45
	ds_read2_b32 v[52:53], v68 offset1:31
	s_waitcnt lgkmcnt(1)
	v_mfma_f32_16x16x32_f16 v[32:35], v[38:41], v[20:23], v[32:35]
	v_sub_u32_e32 v38, v37, v76
	v_max_i32_e32 v38, -15, v38
	v_add_u32_e32 v38, 15, v38
	v_min_u32_e32 v38, 30, v38
	v_lshl_add_u32 v69, v38, 2, s45
	ds_read2_b32 v[54:55], v69 offset1:31
	v_cmp_lt_i32_e64 s[0:1], v42, v60
	s_and_b64 s[0:1], s[0:1], vcc
	s_waitcnt lgkmcnt(1)
	v_add_f32_e32 v32, v32, v52
	v_cndmask_b32_e64 v156, v107, 0, s[0:1]
	v_add_f32_e32 v131, v156, v32
	s_waitcnt lgkmcnt(0)
	v_add_f32_e32 v32, v33, v54
	v_add_u32_e32 v33, 18, v42
	v_cmp_ge_i32_e32 vcc, v37, v60
	v_cmp_lt_i32_e64 s[0:1], v37, v61
	v_sub_u32_e32 v37, v33, v76
	v_max_i32_e32 v37, -15, v37
	v_add_u32_e32 v37, 15, v37
	v_min_u32_e32 v37, 30, v37
	v_lshl_add_u32 v70, v37, 2, s45
	ds_read2_b32 v[56:57], v70 offset1:31
	s_and_b64 s[0:1], vcc, s[0:1]
	v_max3_f32 v44, v127, s34, v128
	v_cndmask_b32_e64 v158, v107, 0, s[0:1]
	v_max3_f32 v36, v44, v129, v130
	v_add_f32_e32 v132, v158, v32
	s_add_i32 s4, s16, 64
	v_max3_f32 v44, v36, v131, v132
	v_cmp_ge_i32_e32 vcc, v33, v60
	v_cmp_lt_i32_e64 s[0:1], v33, v61
	v_add_u32_e32 v33, 19, v42
	v_add_u32_e32 v36, s4, v64
	s_waitcnt lgkmcnt(0)
	v_add_f32_e32 v32, v34, v56
	v_sub_u32_e32 v34, v33, v76
	v_mad_i32_i24 v46, v36, s25, v65
	v_max_i32_e32 v34, -15, v34
	ds_read_b128 v[36:39], v46
	ds_read_b128 v[40:43], v46 offset:64
	v_add_u32_e32 v34, 15, v34
	v_min_u32_e32 v34, 30, v34
	v_lshl_add_u32 v71, v34, 2, s45
	ds_read2_b32 v[58:59], v71 offset1:31
	s_and_b64 s[0:1], vcc, s[0:1]
	v_cndmask_b32_e64 v160, v107, 0, s[0:1]
	v_add_f32_e32 v133, v160, v32
	v_cmp_ge_i32_e32 vcc, v33, v60
	v_cmp_lt_i32_e64 s[0:1], v33, v61
	s_waitcnt lgkmcnt(0)
	v_add_f32_e32 v48, v35, v58
	v_mfma_f32_16x16x32_f16 v[32:35], v[36:39], v[24:27], 0
	ds_read_b128 v[36:39], v46 offset:2304
	s_and_b64 s[0:1], vcc, s[0:1]
	v_cndmask_b32_e64 v170, v107, 0, s[0:1]
	v_mfma_f32_16x16x32_f16 v[32:35], v[40:43], v[20:23], v[32:35]
	ds_read_b128 v[40:43], v46 offset:2368
	v_add_f32_e32 v134, v170, v48
	v_max3_f32 v44, v44, v133, v134
	s_waitcnt lgkmcnt(1)
	v_mfma_f32_16x16x32_f16 v[36:39], v[36:39], v[24:27], 0
	s_add_i32 s5, s16, 0x80
	s_nop 1
	v_add_f32_e32 v32, v32, v45
	v_add_f32_e32 v136, v30, v32
	v_add_f32_e32 v32, v33, v47
	v_add_f32_e32 v33, v34, v49
	v_add_f32_e32 v137, v28, v32
	v_add_f32_e32 v138, v31, v33
	v_add_f32_e32 v33, v35, v51
	v_max3_f32 v32, v44, v136, v137
	v_add_f32_e32 v139, v154, v33
	v_max3_f32 v44, v32, v138, v139
	s_waitcnt lgkmcnt(0)
	v_mfma_f32_16x16x32_f16 v[32:35], v[40:43], v[20:23], v[36:39]
	s_add_i32 s45, s16, 0xc0
	s_add_i32 s46, s16, 0x100
	s_add_i32 s47, s16, 0x140
	s_add_i32 s48, s16, 0x180
	s_add_i32 s49, s16, 0x1c0
	s_nop 2
	v_add_f32_e32 v32, v32, v53
	v_add_f32_e32 v135, v156, v32
	v_add_u32_e32 v32, s5, v64
	v_mad_i32_i24 v52, v32, s25, v65
	ds_read_b128 v[36:39], v52
	ds_read_b128 v[40:43], v52 offset:64
	v_add_f32_e32 v32, v33, v55
	v_add_f32_e32 v140, v158, v32
	v_add_f32_e32 v32, v34, v57
	v_add_f32_e32 v142, v160, v32
	v_add_f32_e32 v32, v35, v59
	v_add_f32_e32 v141, v170, v32
	s_waitcnt lgkmcnt(1)
	v_mfma_f32_16x16x32_f16 v[32:35], v[36:39], v[24:27], 0
	v_max3_f32 v44, v44, v135, v140
	v_max3_f32 v53, v44, v142, v141
	ds_read2_b32 v[44:45], v62 offset0:62 offset1:93
	ds_read2_b32 v[46:47], v63 offset0:62 offset1:93
	s_waitcnt lgkmcnt(2)
	v_mfma_f32_16x16x32_f16 v[32:35], v[40:43], v[20:23], v[32:35]
	ds_read_b128 v[36:39], v52 offset:2304
	ds_read2_b32 v[48:49], v66 offset0:62 offset1:93
	ds_read2_b32 v[50:51], v67 offset0:62 offset1:93
	ds_read_b128 v[40:43], v52 offset:2368
	ds_read2_b32 v[54:55], v69 offset0:62 offset1:93
	s_waitcnt lgkmcnt(6)
	s_nop 1
	v_add_f32_e32 v32, v32, v44
	v_add_f32_e32 v143, v30, v32
	s_waitcnt lgkmcnt(5)
	v_add_f32_e32 v32, v33, v46
	v_add_f32_e32 v144, v28, v32
	s_waitcnt lgkmcnt(3)
	v_add_f32_e32 v32, v34, v48
	v_add_f32_e32 v145, v31, v32
	s_waitcnt lgkmcnt(2)
	v_add_f32_e32 v46, v35, v50
	v_mfma_f32_16x16x32_f16 v[32:35], v[36:39], v[24:27], 0
	v_max3_f32 v44, v53, v143, v144
	ds_read2_b32 v[52:53], v68 offset0:62 offset1:93
	v_add_f32_e32 v146, v154, v46
	s_waitcnt lgkmcnt(2)
	v_mfma_f32_16x16x32_f16 v[32:35], v[40:43], v[20:23], v[32:35]
	ds_read2_b32 v[56:57], v70 offset0:62 offset1:93
	v_max3_f32 v44, v44, v145, v146
	s_waitcnt lgkmcnt(1)
	s_nop 4
	v_add_f32_e32 v32, v32, v52
	v_add_f32_e32 v147, v156, v32
	v_add_u32_e32 v32, s45, v64
	v_mad_i32_i24 v46, v32, s25, v65
	ds_read_b128 v[36:39], v46
	ds_read_b128 v[40:43], v46 offset:64
	ds_read2_b32 v[58:59], v71 offset0:62 offset1:93
	s_waitcnt lgkmcnt(2)
	v_mfma_f32_16x16x32_f16 v[36:39], v[36:39], v[24:27], 0
	v_add_f32_e32 v32, v33, v54
	v_add_f32_e32 v33, v34, v56
	v_add_f32_e32 v148, v158, v32
	v_add_f32_e32 v149, v160, v33
	s_waitcnt lgkmcnt(0)
	v_add_f32_e32 v33, v35, v58
	v_max3_f32 v32, v44, v147, v148
	v_add_f32_e32 v150, v170, v33
	v_max3_f32 v44, v32, v149, v150
	v_mfma_f32_16x16x32_f16 v[32:35], v[40:43], v[20:23], v[36:39]
	ds_read_b128 v[40:43], v46 offset:2368
	s_nop 1
	ds_read_b128 v[36:39], v46 offset:2304
	s_waitcnt lgkmcnt(0)
	v_mfma_f32_16x16x32_f16 v[36:39], v[36:39], v[24:27], 0
	s_nop 1
	v_add_f32_e32 v32, v32, v45
	v_add_f32_e32 v152, v30, v32
	v_add_f32_e32 v32, v33, v47
	v_add_f32_e32 v33, v34, v49
	v_add_f32_e32 v153, v28, v32
	v_add_f32_e32 v155, v31, v33
	v_add_f32_e32 v33, v35, v51
	v_max3_f32 v32, v44, v152, v153
	v_add_f32_e32 v157, v154, v33
	v_max3_f32 v44, v32, v155, v157
	v_mfma_f32_16x16x32_f16 v[32:35], v[40:43], v[20:23], v[36:39]
	s_nop 7
	v_add_f32_e32 v32, v32, v53
	v_add_f32_e32 v151, v156, v32
	v_add_u32_e32 v32, s46, v64
	v_mad_i32_i24 v52, v32, s25, v65
	ds_read_b128 v[36:39], v52
	ds_read_b128 v[40:43], v52 offset:64
	v_add_f32_e32 v32, v33, v55
	v_add_f32_e32 v159, v158, v32
	v_add_f32_e32 v32, v34, v57
	v_add_f32_e32 v192, v160, v32
	v_add_f32_e32 v32, v35, v59
	v_add_f32_e32 v161, v170, v32
	s_waitcnt lgkmcnt(1)
	v_mfma_f32_16x16x32_f16 v[32:35], v[36:39], v[24:27], 0
	v_max3_f32 v44, v44, v151, v159
	v_max3_f32 v53, v44, v192, v161
	ds_read2_b32 v[44:45], v62 offset0:124 offset1:155
	ds_read2_b32 v[46:47], v63 offset0:124 offset1:155
	s_waitcnt lgkmcnt(2)
	v_mfma_f32_16x16x32_f16 v[32:35], v[40:43], v[20:23], v[32:35]
	ds_read_b128 v[36:39], v52 offset:2304
	ds_read2_b32 v[48:49], v66 offset0:124 offset1:155
	ds_read2_b32 v[50:51], v67 offset0:124 offset1:155
	ds_read_b128 v[40:43], v52 offset:2368
	ds_read2_b32 v[54:55], v69 offset0:124 offset1:155
	s_waitcnt lgkmcnt(6)
	s_nop 1
	v_add_f32_e32 v32, v32, v44
	v_add_f32_e32 v193, v30, v32
	s_waitcnt lgkmcnt(5)
	v_add_f32_e32 v32, v33, v46
	v_add_f32_e32 v194, v28, v32
	s_waitcnt lgkmcnt(3)
	v_add_f32_e32 v32, v34, v48
	v_add_f32_e32 v195, v31, v32
	s_waitcnt lgkmcnt(2)
	v_add_f32_e32 v46, v35, v50
	v_mfma_f32_16x16x32_f16 v[32:35], v[36:39], v[24:27], 0
	v_max3_f32 v44, v53, v193, v194
	ds_read2_b32 v[52:53], v68 offset0:124 offset1:155
	v_add_f32_e32 v196, v154, v46
	s_waitcnt lgkmcnt(2)
	v_mfma_f32_16x16x32_f16 v[32:35], v[40:43], v[20:23], v[32:35]
	ds_read2_b32 v[56:57], v70 offset0:124 offset1:155
	v_max3_f32 v44, v44, v195, v196
	s_waitcnt lgkmcnt(1)
	s_nop 4
	v_add_f32_e32 v32, v32, v52
	v_add_f32_e32 v197, v156, v32
	v_add_u32_e32 v32, s47, v64
	v_mad_i32_i24 v46, v32, s25, v65
	ds_read_b128 v[36:39], v46
	ds_read_b128 v[40:43], v46 offset:64
	ds_read2_b32 v[58:59], v71 offset0:124 offset1:155
	s_waitcnt lgkmcnt(2)
	v_mfma_f32_16x16x32_f16 v[36:39], v[36:39], v[24:27], 0
	v_add_f32_e32 v32, v33, v54
	v_add_f32_e32 v33, v34, v56
	v_add_f32_e32 v198, v158, v32
	v_add_f32_e32 v199, v160, v33
	s_waitcnt lgkmcnt(0)
	v_add_f32_e32 v33, v35, v58
	v_max3_f32 v32, v44, v197, v198
	v_add_f32_e32 v200, v170, v33
	v_max3_f32 v44, v32, v199, v200
	v_mfma_f32_16x16x32_f16 v[32:35], v[40:43], v[20:23], v[36:39]
	ds_read_b128 v[40:43], v46 offset:2368
	ds_read2_b32 v[60:61], v62 offset0:186 offset1:217
	s_nop 0
	ds_read_b128 v[36:39], v46 offset:2304
	s_waitcnt lgkmcnt(0)
	v_mfma_f32_16x16x32_f16 v[36:39], v[36:39], v[24:27], 0
	s_nop 1
	v_add_f32_e32 v32, v32, v45
	v_add_f32_e32 v201, v30, v32
	v_add_f32_e32 v32, v33, v47
	v_add_f32_e32 v33, v34, v49
	v_add_f32_e32 v202, v28, v32
	v_add_f32_e32 v203, v31, v33
	v_add_f32_e32 v33, v35, v51
	v_max3_f32 v32, v44, v201, v202
	v_add_f32_e32 v206, v154, v33
	v_max3_f32 v44, v32, v203, v206
	v_mfma_f32_16x16x32_f16 v[32:35], v[40:43], v[20:23], v[36:39]
	s_nop 2
	v_add_u32_e32 v36, s48, v64
	v_mad_i32_i24 v45, v36, s25, v65
	ds_read_b128 v[36:39], v45
	ds_read_b128 v[40:43], v45 offset:64
	s_nop 0
	v_add_f32_e32 v32, v32, v53
	v_add_f32_e32 v207, v156, v32
	v_add_f32_e32 v32, v33, v55
	v_add_f32_e32 v208, v158, v32
	v_add_f32_e32 v32, v34, v57
	v_add_f32_e32 v209, v160, v32
	v_add_f32_e32 v46, v35, v59
	s_waitcnt lgkmcnt(1)
	v_mfma_f32_16x16x32_f16 v[32:35], v[36:39], v[24:27], 0
	ds_read_b128 v[36:39], v45 offset:2304
	v_max3_f32 v44, v44, v207, v208
	v_add_f32_e32 v210, v170, v46
	s_waitcnt lgkmcnt(1)
	v_mfma_f32_16x16x32_f16 v[32:35], v[40:43], v[20:23], v[32:35]
	v_max3_f32 v52, v44, v209, v210
	ds_read2_b32 v[62:63], v63 offset0:186 offset1:217
	ds_read_b128 v[40:43], v45 offset:2368
	s_waitcnt lgkmcnt(2)
	v_mfma_f32_16x16x32_f16 v[36:39], v[36:39], v[24:27], 0
	s_nop 2
	v_add_f32_e32 v32, v32, v60
	v_add_f32_e32 v211, v30, v32
	v_add_u32_e32 v32, s49, v64
	v_mad_i32_i24 v32, v32, s25, v65
	ds_read_b128 v[44:47], v32
	ds_read2_b32 v[64:65], v66 offset0:186 offset1:217
	ds_read_b128 v[48:51], v32 offset:64
	s_waitcnt lgkmcnt(4)
	v_add_f32_e32 v33, v33, v62
	s_waitcnt lgkmcnt(3)
	v_mfma_f32_16x16x32_f16 v[36:39], v[40:43], v[20:23], v[36:39]
	ds_read_b128 v[40:43], v32 offset:2304
	v_add_f32_e32 v212, v28, v33
	v_max3_f32 v56, v52, v211, v212
	s_waitcnt lgkmcnt(3)
	v_mfma_f32_16x16x32_f16 v[44:47], v[44:47], v[24:27], 0
	ds_read2_b32 v[66:67], v67 offset0:186 offset1:217
	ds_read_b128 v[52:55], v32 offset:2368
	v_mul_u32_u24_e32 v32, 0x90, v101
	v_add3_u32 v171, s26, v29, v32
	s_waitcnt lgkmcnt(3)
	v_mfma_f32_16x16x32_f16 v[44:47], v[48:51], v[20:23], v[44:47]
	ds_read_b128 v[48:51], v171
	v_add_f32_e32 v33, v34, v64
	v_add_f32_e32 v213, v31, v33
	s_waitcnt lgkmcnt(2)
	v_add_f32_e32 v29, v35, v66
	ds_read_b128 v[32:35], v171 offset:64
	v_mfma_f32_16x16x32_f16 v[40:43], v[40:43], v[24:27], 0
	v_add_f32_e32 v214, v154, v29
	v_max3_f32 v29, v56, v213, v214
	s_waitcnt lgkmcnt(2)
	v_mfma_f32_16x16x32_f16 v[40:43], v[52:55], v[20:23], v[40:43]
	ds_read2_b32 v[162:163], v68 offset0:186 offset1:217
	ds_read_b128 v[52:55], v171 offset:2304
	ds_read2_b32 v[164:165], v69 offset0:186 offset1:217
	ds_read_b128 v[56:59], v171 offset:2368
	ds_read2_b32 v[166:167], v70 offset0:186 offset1:217
	s_waitcnt lgkmcnt(6)
	v_mfma_f32_16x16x32_f16 v[48:51], v[48:51], v[24:27], 0
	ds_read2_b32 v[168:169], v71 offset0:186 offset1:217
	s_waitcnt lgkmcnt(5)
	v_add_f32_e32 v40, v40, v163
	v_add_f32_e32 v223, v156, v40
	v_mfma_f32_16x16x32_f16 v[84:87], v[32:35], v[20:23], v[48:51]
	v_add_f32_e32 v32, v36, v162
	v_add_f32_e32 v215, v156, v32
	ds_read_b128 v[32:35], v171 offset:4608
	s_waitcnt lgkmcnt(5)
	v_mfma_f32_16x16x32_f16 v[48:51], v[52:55], v[24:27], 0
	ds_read_b128 v[52:55], v171 offset:4672
	s_waitcnt lgkmcnt(5)
	v_add_f32_e32 v36, v37, v164
	v_add_f32_e32 v216, v158, v36
	s_waitcnt lgkmcnt(4)
	v_mfma_f32_16x16x32_f16 v[80:83], v[56:59], v[20:23], v[48:51]
	ds_read_b128 v[56:59], v171 offset:6976
	s_waitcnt lgkmcnt(4)
	v_add_f32_e32 v36, v38, v166
	v_add_f32_e32 v217, v160, v36
	ds_read_b128 v[48:51], v171 offset:6912
	s_waitcnt lgkmcnt(3)
	v_mfma_f32_16x16x32_f16 v[32:35], v[32:35], v[24:27], 0
	v_max3_f32 v29, v29, v215, v216
	s_waitcnt lgkmcnt(2)
	v_mfma_f32_16x16x32_f16 v[76:79], v[52:55], v[20:23], v[32:35]
	v_add_f32_e32 v52, v39, v168
	v_add_f32_e32 v218, v170, v52
	ds_read_b128 v[52:55], v171 offset:11584
	s_nop 1
	ds_read_b128 v[32:35], v171 offset:9216
	s_waitcnt lgkmcnt(2)
	v_mfma_f32_16x16x32_f16 v[36:39], v[48:51], v[24:27], 0
	ds_read_b128 v[48:51], v171 offset:9280
	v_max3_f32 v29, v29, v217, v218
	v_mfma_f32_16x16x32_f16 v[72:75], v[56:59], v[20:23], v[36:39]
	s_waitcnt lgkmcnt(1)
	v_mfma_f32_16x16x32_f16 v[32:35], v[32:35], v[24:27], 0
	s_nop 2
	v_add_f32_e32 v36, v44, v61
	v_add_f32_e32 v219, v30, v36
	ds_read_b128 v[36:39], v171 offset:11520
	s_waitcnt lgkmcnt(1)
	v_mfma_f32_16x16x32_f16 v[68:71], v[48:51], v[20:23], v[32:35]
	v_add_f32_e32 v30, v45, v63
	v_add_f32_e32 v220, v28, v30
	v_add_f32_e32 v28, v46, v65
	ds_read_b128 v[32:35], v171 offset:13824
	s_waitcnt lgkmcnt(1)
	v_mfma_f32_16x16x32_f16 v[36:39], v[36:39], v[24:27], 0
	v_max3_f32 v44, v29, v219, v220
	v_add_f32_e32 v221, v31, v28
	ds_read_b128 v[28:31], v171 offset:13888
	v_add_f32_e32 v45, v47, v67
	v_mfma_f32_16x16x32_f16 v[64:67], v[52:55], v[20:23], v[36:39]
	v_add_f32_e32 v222, v154, v45
	v_max3_f32 v48, v44, v221, v222
	ds_read_b128 v[44:47], v171 offset:16192
	ds_read_b128 v[36:39], v171 offset:16128
	s_waitcnt lgkmcnt(3)
	v_mfma_f32_16x16x32_f16 v[32:35], v[32:35], v[24:27], 0
	s_waitcnt lgkmcnt(2)
	v_mfma_f32_16x16x32_f16 v[60:63], v[28:31], v[20:23], v[32:35]
	v_add_f32_e32 v28, v41, v165
	v_add_f32_e32 v224, v158, v28
	ds_read_b128 v[28:31], v171 offset:18432
	s_waitcnt lgkmcnt(1)
	v_mfma_f32_16x16x32_f16 v[32:35], v[36:39], v[24:27], 0
	ds_read_b128 v[36:39], v171 offset:18496
	v_add_f32_e32 v41, v42, v167
	v_add_f32_e32 v225, v160, v41
	v_mfma_f32_16x16x32_f16 v[56:59], v[44:47], v[20:23], v[32:35]
	v_add_f32_e32 v41, v43, v169
	v_max3_f32 v40, v48, v223, v224
	v_add_f32_e32 v226, v170, v41
	s_nop 0
	ds_read_b128 v[32:35], v171 offset:20736
	v_max3_f32 v44, v40, v225, v226
	ds_read_b128 v[40:43], v171 offset:20800
	s_waitcnt lgkmcnt(3)
	v_mfma_f32_16x16x32_f16 v[28:31], v[28:31], v[24:27], 0
	ds_read_b128 v[162:165], v171 offset:30016
	ds_read_b128 v[166:169], v171 offset:32320
	s_waitcnt lgkmcnt(4)
	v_mfma_f32_16x16x32_f16 v[52:55], v[36:39], v[20:23], v[28:31]
	s_waitcnt lgkmcnt(3)
	v_mfma_f32_16x16x32_f16 v[32:35], v[32:35], v[24:27], 0
	s_nop 1
	v_max3_f32 v28, v44, v84, v85
	v_max3_f32 v36, v28, v86, v87
	ds_read_b128 v[28:31], v171 offset:23040
	v_max3_f32 v36, v36, v80, v81
	v_max3_f32 v44, v36, v82, v83
	s_waitcnt lgkmcnt(3)
	v_mfma_f32_16x16x32_f16 v[48:51], v[40:43], v[20:23], v[32:35]
	ds_read_b128 v[36:39], v171 offset:23104
	s_nop 1
	v_max3_f32 v32, v44, v76, v77
	v_max3_f32 v40, v32, v78, v79
	ds_read_b128 v[32:35], v171 offset:25344
	v_max3_f32 v40, v40, v72, v73
	v_max3_f32 v154, v40, v74, v75
	ds_read_b128 v[40:43], v171 offset:25408
	s_waitcnt lgkmcnt(3)
	v_mfma_f32_16x16x32_f16 v[28:31], v[28:31], v[24:27], 0
	s_waitcnt lgkmcnt(2)
	v_mfma_f32_16x16x32_f16 v[44:47], v[36:39], v[20:23], v[28:31]
	s_waitcnt lgkmcnt(1)
	v_mfma_f32_16x16x32_f16 v[32:35], v[32:35], v[24:27], 0
	s_nop 3
	v_max3_f32 v28, v154, v68, v69
	v_max3_f32 v36, v28, v70, v71
	v_max3_f32 v36, v36, v64, v65
	v_max3_f32 v154, v36, v66, v67
	s_waitcnt lgkmcnt(0)
	v_mfma_f32_16x16x32_f16 v[40:43], v[40:43], v[20:23], v[32:35]
	ds_read_b128 v[36:39], v171 offset:27712
	ds_read_b128 v[28:31], v171 offset:27648
	s_nop 0
	v_max3_f32 v32, v154, v60, v61
	v_max3_f32 v154, v32, v62, v63
	ds_read_b128 v[32:35], v171 offset:29952
	s_waitcnt lgkmcnt(0)
	v_mfma_f32_16x16x32_f16 v[32:35], v[32:35], v[24:27], 0
	v_max3_f32 v154, v154, v56, v57
	v_max3_f32 v154, v154, v58, v59
	v_mfma_f32_16x16x32_f16 v[32:35], v[162:165], v[20:23], v[32:35]
	ds_read_b128 v[162:165], v171 offset:34560
	v_mfma_f32_16x16x32_f16 v[28:31], v[28:31], v[24:27], 0
	v_mfma_f32_16x16x32_f16 v[36:39], v[36:39], v[20:23], v[28:31]
	s_nop 6
	v_max3_f32 v28, v154, v52, v53
	v_max3_f32 v154, v28, v54, v55
	ds_read_b128 v[28:31], v171 offset:32256
	ds_read_b128 v[170:173], v171 offset:34624
	v_max3_f32 v154, v154, v48, v49
	v_max3_f32 v154, v154, v50, v51
	v_max3_f32 v154, v154, v44, v45
	s_waitcnt lgkmcnt(1)
	v_mfma_f32_16x16x32_f16 v[28:31], v[28:31], v[24:27], 0
	v_max3_f32 v154, v154, v46, v47
	v_max3_f32 v154, v154, v40, v41
	v_max3_f32 v154, v154, v42, v43
	v_mfma_f32_16x16x32_f16 v[24:27], v[162:165], v[24:27], 0
	v_max3_f32 v154, v154, v36, v37
	v_max3_f32 v154, v154, v38, v39
	v_max3_f32 v154, v154, v32, v33
	v_mfma_f32_16x16x32_f16 v[28:31], v[166:169], v[20:23], v[28:31]
	v_max3_f32 v154, v154, v34, v35
	s_waitcnt lgkmcnt(0)
	v_mfma_f32_16x16x32_f16 v[20:23], v[170:173], v[20:23], v[24:27]
	s_nop 4
	v_max3_f32 v154, v154, v28, v29
	v_max3_f32 v154, v154, v30, v31
	s_nop 0
	v_max3_f32 v24, v154, v20, v21
	v_max3_f32 v24, v24, v22, v23
	ds_bpermute_b32 v25, v113, v24
	s_waitcnt lgkmcnt(0)
	v_max_f32_e32 v25, v25, v25
	v_max_f32_e32 v24, v24, v25
	ds_bpermute_b32 v25, v112, v24
	s_waitcnt lgkmcnt(0)
	v_max_f32_e32 v25, v25, v25
	v_max_f32_e32 v227, v24, v25
	v_sub_f32_e32 v24, v127, v227
	v_exp_f32_e32 v177, v24
	v_sub_f32_e32 v24, v128, v227
	v_exp_f32_e32 v179, v24
	v_sub_f32_e32 v24, v129, v227
	v_exp_f32_e32 v181, v24
	v_sub_f32_e32 v24, v130, v227
	v_exp_f32_e32 v183, v24
	v_sub_f32_e32 v25, v131, v227
	v_add_f32_e32 v24, 0, v177
	v_exp_f32_e32 v188, v25
	v_sub_f32_e32 v25, v132, v227
	v_add_f32_e32 v24, v179, v24
	v_exp_f32_e32 v189, v25
	v_sub_f32_e32 v25, v133, v227
	v_add_f32_e32 v24, v181, v24
	v_exp_f32_e32 v190, v25
	v_sub_f32_e32 v25, v134, v227
	v_add_f32_e32 v24, v183, v24
	v_exp_f32_e32 v191, v25
	v_sub_f32_e32 v25, v136, v227
	v_add_f32_e32 v24, v188, v24
	v_exp_f32_e32 v168, v25
	v_sub_f32_e32 v25, v137, v227
	v_add_f32_e32 v24, v189, v24
	v_exp_f32_e32 v170, v25
	v_sub_f32_e32 v25, v138, v227
	v_add_f32_e32 v24, v190, v24
	v_exp_f32_e32 v172, v25
	v_sub_f32_e32 v25, v139, v227
	v_add_f32_e32 v24, v191, v24
	v_exp_f32_e32 v174, v25
	v_sub_f32_e32 v25, v135, v227
	v_add_f32_e32 v24, v168, v24
	v_exp_f32_e32 v184, v25
	v_sub_f32_e32 v25, v140, v227
	v_add_f32_e32 v24, v170, v24
	v_exp_f32_e32 v185, v25
	v_sub_f32_e32 v25, v142, v227
	v_add_f32_e32 v24, v172, v24
	v_exp_f32_e32 v186, v25
	v_sub_f32_e32 v25, v141, v227
	v_add_f32_e32 v24, v174, v24
	v_exp_f32_e32 v187, v25
	v_sub_f32_e32 v25, v143, v227
	v_add_f32_e32 v24, v184, v24
	v_exp_f32_e32 v160, v25
	v_sub_f32_e32 v25, v144, v227
	v_add_f32_e32 v24, v185, v24
	v_exp_f32_e32 v162, v25
	v_sub_f32_e32 v25, v145, v227
	v_add_f32_e32 v24, v186, v24
	v_exp_f32_e32 v164, v25
	v_sub_f32_e32 v25, v146, v227
	v_add_f32_e32 v24, v187, v24
	v_exp_f32_e32 v166, v25
	v_sub_f32_e32 v25, v147, v227
	v_add_f32_e32 v24, v160, v24
	v_exp_f32_e32 v175, v25
	v_sub_f32_e32 v25, v148, v227
	v_add_f32_e32 v24, v162, v24
	v_exp_f32_e32 v178, v25
	v_sub_f32_e32 v25, v149, v227
	v_add_f32_e32 v24, v164, v24
	v_exp_f32_e32 v180, v25
	v_sub_f32_e32 v25, v150, v227
	v_add_f32_e32 v24, v166, v24
	v_exp_f32_e32 v182, v25
	v_sub_f32_e32 v25, v152, v227
	v_add_f32_e32 v24, v175, v24
	v_exp_f32_e32 v152, v25
	v_sub_f32_e32 v25, v153, v227
	v_add_f32_e32 v24, v178, v24
	v_exp_f32_e32 v154, v25
	v_sub_f32_e32 v25, v155, v227
	v_add_f32_e32 v24, v180, v24
	v_exp_f32_e32 v156, v25
	v_sub_f32_e32 v25, v157, v227
	v_add_f32_e32 v24, v182, v24
	v_exp_f32_e32 v158, v25
	v_sub_f32_e32 v25, v151, v227
	v_add_f32_e32 v24, v152, v24
	v_exp_f32_e32 v167, v25
	v_sub_f32_e32 v25, v159, v227
	v_add_f32_e32 v24, v154, v24
	v_exp_f32_e32 v169, v25
	v_sub_f32_e32 v25, v192, v227
	v_add_f32_e32 v24, v156, v24
	v_exp_f32_e32 v171, v25
	v_sub_f32_e32 v25, v161, v227
	v_add_f32_e32 v24, v158, v24
	v_exp_f32_e32 v173, v25
	v_sub_f32_e32 v25, v193, v227
	v_add_f32_e32 v24, v167, v24
	v_exp_f32_e32 v144, v25
	v_sub_f32_e32 v25, v194, v227
	v_add_f32_e32 v24, v169, v24
	v_exp_f32_e32 v146, v25
	v_sub_f32_e32 v25, v195, v227
	v_add_f32_e32 v24, v171, v24
	v_exp_f32_e32 v148, v25
	v_sub_f32_e32 v25, v196, v227
	v_add_f32_e32 v24, v173, v24
	v_exp_f32_e32 v150, v25
	v_sub_f32_e32 v25, v197, v227
	v_add_f32_e32 v24, v144, v24
	v_exp_f32_e32 v159, v25
	v_sub_f32_e32 v25, v198, v227
	v_add_f32_e32 v24, v146, v24
	v_exp_f32_e32 v161, v25
	v_sub_f32_e32 v25, v199, v227
	v_add_f32_e32 v24, v148, v24
	v_exp_f32_e32 v163, v25
	v_sub_f32_e32 v25, v200, v227
	v_add_f32_e32 v24, v150, v24
	v_exp_f32_e32 v165, v25
	v_sub_f32_e32 v25, v201, v227
	v_add_f32_e32 v24, v159, v24
	v_exp_f32_e32 v136, v25
	v_sub_f32_e32 v25, v202, v227
	v_add_f32_e32 v24, v161, v24
	v_exp_f32_e32 v138, v25
	v_sub_f32_e32 v25, v203, v227
	v_add_f32_e32 v24, v163, v24
	v_exp_f32_e32 v140, v25
	v_sub_f32_e32 v25, v206, v227
	v_add_f32_e32 v24, v165, v24
	v_exp_f32_e32 v142, v25
	v_sub_f32_e32 v25, v207, v227
	v_add_f32_e32 v24, v136, v24
	v_exp_f32_e32 v151, v25
	v_sub_f32_e32 v25, v208, v227
	v_add_f32_e32 v24, v138, v24
	v_exp_f32_e32 v153, v25
	v_sub_f32_e32 v25, v209, v227
	v_add_f32_e32 v24, v140, v24
	v_exp_f32_e32 v155, v25
	v_sub_f32_e32 v25, v210, v227
	v_add_f32_e32 v24, v142, v24
	v_exp_f32_e32 v157, v25
	v_sub_f32_e32 v25, v211, v227
	v_add_f32_e32 v24, v151, v24
	v_exp_f32_e32 v131, v25
	v_sub_f32_e32 v25, v212, v227
	v_add_f32_e32 v24, v153, v24
	v_exp_f32_e32 v132, v25
	v_sub_f32_e32 v25, v213, v227
	v_add_f32_e32 v24, v155, v24
	v_exp_f32_e32 v133, v25
	v_sub_f32_e32 v25, v214, v227
	v_add_f32_e32 v24, v157, v24
	v_exp_f32_e32 v134, v25
	v_sub_f32_e32 v25, v215, v227
	v_add_f32_e32 v24, v131, v24
	v_exp_f32_e32 v143, v25
	v_sub_f32_e32 v25, v216, v227
	v_add_f32_e32 v24, v132, v24
	v_exp_f32_e32 v145, v25
	v_sub_f32_e32 v25, v217, v227
	v_add_f32_e32 v24, v133, v24
	v_exp_f32_e32 v147, v25
	v_sub_f32_e32 v25, v218, v227
	v_add_f32_e32 v24, v134, v24
	v_exp_f32_e32 v149, v25
	v_sub_f32_e32 v25, v219, v227
	v_add_f32_e32 v24, v143, v24
	v_exp_f32_e32 v127, v25
	v_sub_f32_e32 v25, v220, v227
	v_add_f32_e32 v24, v145, v24
	v_exp_f32_e32 v128, v25
	v_sub_f32_e32 v25, v221, v227
	v_add_f32_e32 v24, v147, v24
	v_exp_f32_e32 v129, v25
	v_sub_f32_e32 v25, v222, v227
	v_add_f32_e32 v24, v149, v24
	v_exp_f32_e32 v130, v25
	v_sub_f32_e32 v25, v223, v227
	v_add_f32_e32 v24, v127, v24
	v_exp_f32_e32 v135, v25
	v_sub_f32_e32 v25, v224, v227
	v_add_f32_e32 v24, v128, v24
	v_exp_f32_e32 v137, v25
	v_sub_f32_e32 v25, v225, v227
	v_add_f32_e32 v24, v129, v24
	v_exp_f32_e32 v139, v25
	v_ashrrev_i32_e32 v228, 9, v111
	v_add_u32_e32 v229, s41, v228
	v_min_i32_e32 v229, 0x7f, v229
	v_lshl_add_u32 v230, v229, 6, v110
	v_ashrrev_i32_e32 v229, 9, v116
	v_add_u32_e32 v111, s41, v229
	v_min_i32_e32 v111, 0x7f, v111
	s_add_u32 s0, s14, s44
	v_lshl_add_u32 v236, v111, 6, v110
	s_addc_u32 s1, s15, 0
	v_ashrrev_i32_e32 v231, 31, v230
	v_ashrrev_i32_e32 v237, 31, v236
	v_lshl_add_u64 v[222:223], s[0:1], 0, v[88:89]
	v_lshlrev_b64 v[230:231], 11, v[230:231]
	v_lshlrev_b64 v[236:237], 11, v[236:237]
	v_lshl_add_u64 v[230:231], v[222:223], 0, v[230:231]
	v_lshl_add_u64 v[196:197], v[222:223], 0, v[236:237]
	v_ashrrev_i32_e32 v111, 9, v118
	global_load_dwordx4 v[232:235], v[230:231], off
	s_nop 0
	global_load_dwordx4 v[196:199], v[196:197], off
	v_add_u32_e32 v230, s41, v111
	v_min_i32_e32 v230, 0x7f, v230
	v_lshl_add_u32 v230, v230, 6, v110
	v_ashrrev_i32_e32 v231, 31, v230
	v_lshlrev_b64 v[230:231], 11, v[230:231]
	v_lshl_add_u64 v[200:201], v[222:223], 0, v[230:231]
	v_ashrrev_i32_e32 v230, 9, v120
	v_add_u32_e32 v231, s41, v230
	v_min_i32_e32 v231, 0x7f, v231
	v_lshl_add_u32 v202, v231, 6, v110
	v_ashrrev_i32_e32 v231, 9, v121
	v_add_u32_e32 v116, s41, v231
	v_min_i32_e32 v116, 0x7f, v116
	v_lshl_add_u32 v120, v116, 6, v110
	v_ashrrev_i32_e32 v203, 31, v202
	v_ashrrev_i32_e32 v121, 31, v120
	v_lshlrev_b64 v[202:203], 11, v[202:203]
	v_lshlrev_b64 v[120:121], 11, v[120:121]
	v_lshl_add_u64 v[206:207], v[222:223], 0, v[202:203]
	v_lshl_add_u64 v[120:121], v[222:223], 0, v[120:121]
	v_lshl_add_u64 v[98:99], v[222:223], 0, v[98:99]
	v_lshl_add_u64 v[96:97], v[222:223], 0, v[96:97]
	global_load_dwordx4 v[200:203], v[200:201], off
	s_nop 0
	global_load_dwordx4 v[206:209], v[206:207], off
	s_nop 0
	global_load_dwordx4 v[210:213], v[120:121], off
	global_load_dwordx4 v[214:217], v[98:99], off
	v_lshl_add_u64 v[98:99], v[222:223], 0, v[94:95]
	global_load_dwordx4 v[94:97], v[96:97], off
	s_nop 0
	global_load_dwordx4 v[218:221], v[98:99], off
	v_lshl_add_u64 v[92:93], v[222:223], 0, v[92:93]
	global_load_dwordx4 v[222:225], v[92:93], off
	v_sub_f32_e32 v25, v226, v227
	v_add_f32_e32 v24, v130, v24
	v_exp_f32_e32 v141, v25
	v_sub_f32_e32 v25, v84, v227
	v_add_f32_e32 v24, v135, v24
	v_exp_f32_e32 v84, v25
	v_sub_f32_e32 v25, v85, v227
	v_add_f32_e32 v24, v137, v24
	v_exp_f32_e32 v85, v25
	v_sub_f32_e32 v25, v86, v227
	v_add_f32_e32 v24, v139, v24
	v_exp_f32_e32 v86, v25
	v_sub_f32_e32 v25, v87, v227
	v_add_f32_e32 v24, v141, v24
	v_exp_f32_e32 v87, v25
	v_sub_f32_e32 v25, v80, v227
	v_add_f32_e32 v24, v84, v24
	v_exp_f32_e32 v80, v25
	v_sub_f32_e32 v25, v81, v227
	v_add_f32_e32 v24, v85, v24
	v_exp_f32_e32 v81, v25
	v_sub_f32_e32 v25, v82, v227
	v_add_f32_e32 v24, v86, v24
	v_exp_f32_e32 v82, v25
	v_sub_f32_e32 v25, v83, v227
	v_add_f32_e32 v24, v87, v24
	v_exp_f32_e32 v83, v25
	v_sub_f32_e32 v25, v76, v227
	v_add_f32_e32 v24, v80, v24
	v_exp_f32_e32 v76, v25
	v_sub_f32_e32 v25, v77, v227
	v_add_f32_e32 v24, v81, v24
	v_exp_f32_e32 v77, v25
	v_sub_f32_e32 v25, v78, v227
	v_add_f32_e32 v24, v82, v24
	v_exp_f32_e32 v78, v25
	v_sub_f32_e32 v25, v79, v227
	v_add_f32_e32 v24, v83, v24
	v_exp_f32_e32 v79, v25
	v_sub_f32_e32 v25, v72, v227
	v_add_f32_e32 v24, v76, v24
	v_exp_f32_e32 v72, v25
	v_sub_f32_e32 v25, v73, v227
	v_add_f32_e32 v24, v77, v24
	v_exp_f32_e32 v73, v25
	v_sub_f32_e32 v25, v74, v227
	v_add_f32_e32 v24, v78, v24
	v_exp_f32_e32 v74, v25
	v_sub_f32_e32 v25, v75, v227
	v_add_f32_e32 v24, v79, v24
	v_exp_f32_e32 v75, v25
	v_sub_f32_e32 v25, v68, v227
	v_add_f32_e32 v24, v72, v24
	v_exp_f32_e32 v68, v25
	v_sub_f32_e32 v25, v69, v227
	v_add_f32_e32 v24, v73, v24
	v_exp_f32_e32 v69, v25
	v_sub_f32_e32 v25, v70, v227
	v_add_f32_e32 v24, v74, v24
	v_exp_f32_e32 v70, v25
	v_sub_f32_e32 v25, v71, v227
	v_add_f32_e32 v24, v75, v24
	v_exp_f32_e32 v71, v25
	v_sub_f32_e32 v25, v64, v227
	v_add_f32_e32 v24, v68, v24
	v_exp_f32_e32 v64, v25
	v_sub_f32_e32 v25, v65, v227
	v_add_f32_e32 v24, v69, v24
	v_exp_f32_e32 v65, v25
	v_sub_f32_e32 v25, v66, v227
	v_add_f32_e32 v24, v70, v24
	v_exp_f32_e32 v66, v25
	v_sub_f32_e32 v25, v67, v227
	v_add_f32_e32 v24, v71, v24
	v_exp_f32_e32 v67, v25
	v_sub_f32_e32 v25, v60, v227
	v_add_f32_e32 v24, v64, v24
	v_exp_f32_e32 v60, v25
	v_sub_f32_e32 v25, v61, v227
	v_add_f32_e32 v24, v65, v24
	v_exp_f32_e32 v61, v25
	v_sub_f32_e32 v25, v62, v227
	v_add_f32_e32 v24, v66, v24
	v_exp_f32_e32 v62, v25
	v_sub_f32_e32 v25, v63, v227
	v_add_f32_e32 v24, v67, v24
	v_exp_f32_e32 v63, v25
	v_sub_f32_e32 v25, v56, v227
	v_add_f32_e32 v24, v60, v24
	v_exp_f32_e32 v56, v25
	v_sub_f32_e32 v25, v57, v227
	v_add_f32_e32 v24, v61, v24
	v_exp_f32_e32 v57, v25
	v_sub_f32_e32 v25, v58, v227
	v_add_f32_e32 v24, v62, v24
	v_exp_f32_e32 v58, v25
	v_sub_f32_e32 v25, v59, v227
	v_add_f32_e32 v24, v63, v24
	v_exp_f32_e32 v59, v25
	v_sub_f32_e32 v25, v52, v227
	v_add_f32_e32 v24, v56, v24
	v_exp_f32_e32 v52, v25
	v_sub_f32_e32 v25, v53, v227
	v_add_f32_e32 v24, v57, v24
	v_exp_f32_e32 v53, v25
	v_sub_f32_e32 v25, v54, v227
	v_add_f32_e32 v24, v58, v24
	v_exp_f32_e32 v54, v25
	v_sub_f32_e32 v25, v55, v227
	v_add_f32_e32 v24, v59, v24
	v_exp_f32_e32 v55, v25
	v_sub_f32_e32 v25, v48, v227
	v_add_f32_e32 v24, v52, v24
	v_exp_f32_e32 v48, v25
	v_sub_f32_e32 v25, v49, v227
	v_add_f32_e32 v24, v53, v24
	v_exp_f32_e32 v49, v25
	v_sub_f32_e32 v25, v50, v227
	v_add_f32_e32 v24, v54, v24
	v_exp_f32_e32 v50, v25
	v_sub_f32_e32 v25, v51, v227
	v_add_f32_e32 v24, v55, v24
	v_exp_f32_e32 v51, v25
	v_sub_f32_e32 v25, v44, v227
	v_add_f32_e32 v24, v48, v24
	v_exp_f32_e32 v44, v25
	v_sub_f32_e32 v25, v45, v227
	v_add_f32_e32 v24, v49, v24
	v_exp_f32_e32 v45, v25
	v_sub_f32_e32 v25, v46, v227
	v_add_f32_e32 v24, v50, v24
	v_exp_f32_e32 v46, v25
	v_sub_f32_e32 v25, v47, v227
	v_add_f32_e32 v24, v51, v24
	v_exp_f32_e32 v47, v25
	v_sub_f32_e32 v25, v40, v227
	v_add_f32_e32 v24, v44, v24
	v_exp_f32_e32 v40, v25
	v_sub_f32_e32 v25, v41, v227
	v_add_f32_e32 v24, v45, v24
	v_exp_f32_e32 v41, v25
	v_sub_f32_e32 v25, v42, v227
	v_add_f32_e32 v24, v46, v24
	v_exp_f32_e32 v42, v25
	v_sub_f32_e32 v25, v43, v227
	v_add_f32_e32 v24, v47, v24
	v_exp_f32_e32 v43, v25
	v_sub_f32_e32 v25, v36, v227
	v_add_f32_e32 v24, v40, v24
	v_exp_f32_e32 v36, v25
	v_sub_f32_e32 v25, v37, v227
	v_add_f32_e32 v24, v41, v24
	v_exp_f32_e32 v37, v25
	v_sub_f32_e32 v25, v38, v227
	v_add_f32_e32 v24, v42, v24
	v_exp_f32_e32 v38, v25
	v_sub_f32_e32 v25, v39, v227
	v_add_f32_e32 v24, v43, v24
	v_exp_f32_e32 v39, v25
	v_sub_f32_e32 v25, v32, v227
	v_add_f32_e32 v24, v36, v24
	v_exp_f32_e32 v32, v25
	v_sub_f32_e32 v25, v33, v227
	v_add_f32_e32 v24, v37, v24
	v_exp_f32_e32 v33, v25
	v_sub_f32_e32 v25, v34, v227
	v_add_f32_e32 v24, v38, v24
	v_exp_f32_e32 v34, v25
	v_sub_f32_e32 v25, v35, v227
	v_add_f32_e32 v24, v39, v24
	v_exp_f32_e32 v35, v25
	v_add_f32_e32 v24, v32, v24
	v_add_f32_e32 v24, v33, v24
	v_add_f32_e32 v24, v34, v24
	v_add_f32_e32 v192, v35, v24
	v_sub_f32_e32 v24, v28, v227
	v_exp_f32_e32 v24, v24
	v_sub_f32_e32 v25, v29, v227
	v_exp_f32_e32 v25, v25
	v_sub_f32_e32 v26, v30, v227
	v_exp_f32_e32 v26, v26
	v_sub_f32_e32 v27, v31, v227
	v_exp_f32_e32 v27, v27
	v_add_f32_e32 v28, v24, v192
	v_add_f32_e32 v28, v25, v28
	v_add_f32_e32 v28, v26, v28
	v_sub_f32_e32 v20, v20, v227
	v_add_f32_e32 v29, v27, v28
	v_exp_f32_e32 v28, v20
	v_sub_f32_e32 v20, v21, v227
	v_exp_f32_e32 v21, v20
	v_sub_f32_e32 v20, v22, v227
	v_exp_f32_e32 v22, v20
	v_sub_f32_e32 v20, v23, v227
	v_exp_f32_e32 v23, v20
	v_add_f32_e32 v20, v28, v29
	v_add_f32_e32 v20, v21, v20
	v_add_f32_e32 v20, v22, v20
	v_add_f32_e32 v20, v23, v20
	ds_bpermute_b32 v29, v113, v20
	s_waitcnt lgkmcnt(0)
	v_add_f32_e32 v20, v20, v29
	ds_bpermute_b32 v29, v112, v20
	v_mov_b32_e32 v30, v228
	v_mov_b32_e32 v31, v229
	v_mov_b32_e32 v112, v230
	v_mov_b32_e32 v113, v231
	s_waitcnt lgkmcnt(0)
	s_barrier
	s_waitcnt vmcnt(8)
	ds_write_b128 v114, v[232:235]
	s_waitcnt vmcnt(7)
	ds_write_b128 v115, v[196:199]
	s_waitcnt vmcnt(6)
	ds_write_b128 v117, v[200:203]
	s_waitcnt vmcnt(5)
	ds_write_b128 v119, v[206:209]
	s_waitcnt vmcnt(4)
	ds_write_b128 v122, v[210:213]
	s_waitcnt vmcnt(3)
	ds_write_b128 v123, v[214:217]
	s_waitcnt vmcnt(2)
	ds_write_b128 v124, v[94:97]
	s_waitcnt vmcnt(1)
	ds_write_b128 v125, v[218:221]
	s_waitcnt vmcnt(0)
	ds_write_b128 v126, v[222:225]
	s_add_i32 s41, s97, s9
	s_waitcnt lgkmcnt(0)
	s_barrier
	s_cmpk_gt_i32 s41, 0x7ff
	s_cselect_b64 s[0:1], -1, 0
	s_and_b64 vcc, exec, s[0:1]
	s_cbranch_vccnz .LBB0_1405
	s_mov_b64 s[2:3], -1
	s_and_b64 vcc, exec, s[10:11]
	s_cbranch_vccz .LBB0_1422
	s_and_b32 s50, s41, 63
	s_ashr_i32 s44, s41, 6
	s_mov_b64 s[2:3], 0
